# nt (streaming) hint on the read-once f32 weight loads and x loads of P0 so the bf16 copies stay in MALL, on v85
# speedup vs baseline: 1.0107x; 1.0107x over previous
; __device__ __forceinline__ void tr_load(const TrDesc& d, float (&v)[32], int lane) {
; #pragma unroll
;     for (int i = 0; i < 32; ++i) { const int kk = 2 * i + (lane >> 5); v[i] = d.W[(size_t)(d.k0 + kk) * d.ldw + d.n0 + (lane & 31)]; }
; }
; __global__ void __launch_bounds__(NTHREADS, 2) mega_fwd(Args a) {
;     ...
;         if (gw < NITEMS) {
;             TrDesc dc; P0_DESC(gw, dc); float vc[32]; tr_load(dc, vc, lane);
.LBB0_61:
	v_readlane_b32 s5, v249, 18
	s_lshl_b32 s5, s5, 14
	s_ashr_i32 s13, s12, 31
	s_add_i32 s5, s5, 0
	v_lshrrev_b32_e32 v68, 5, v196
	s_lshl_b64 s[12:13], s[12:13], 2
	v_and_b32_e32 v66, 31, v197
	s_add_u32 s10, s10, s12
	v_add_u32_e32 v40, s4, v68
	v_mov_b32_e32 v65, 0
	s_addc_u32 s11, s11, s13
	v_lshlrev_b32_e32 v64, 2, v66
	v_ashrrev_i32_e32 v0, 31, v40
	v_lshl_add_u64 v[24:25], s[10:11], 0, v[64:65]
	v_mul_lo_u32 v2, s6, v0
	v_mul_lo_u32 v3, s7, v40
	v_mad_u64_u32 v[0:1], s[10:11], s6, v40, 0
	v_add3_u32 v1, v1, v2, v3
	v_add_u32_e32 v2, 2, v40
	v_ashrrev_i32_e32 v3, 31, v2
	v_mul_lo_u32 v4, s6, v3
	v_mul_lo_u32 v5, s7, v2
	v_mad_u64_u32 v[2:3], s[10:11], s6, v2, 0
	v_add3_u32 v3, v3, v4, v5
	v_add_u32_e32 v4, 4, v40
	v_ashrrev_i32_e32 v5, 31, v4
	v_mul_lo_u32 v6, s6, v5
	v_mul_lo_u32 v7, s7, v4
	v_mad_u64_u32 v[4:5], s[10:11], s6, v4, 0
	v_add3_u32 v5, v5, v6, v7
	v_add_u32_e32 v6, 6, v40
	v_ashrrev_i32_e32 v7, 31, v6
	v_mul_lo_u32 v8, s6, v7
	v_mul_lo_u32 v9, s7, v6
	v_mad_u64_u32 v[6:7], s[10:11], s6, v6, 0
	v_add3_u32 v7, v7, v8, v9
	v_add_u32_e32 v8, 8, v40
	v_ashrrev_i32_e32 v9, 31, v8
	v_mul_lo_u32 v10, s6, v9
	v_mul_lo_u32 v11, s7, v8
	v_mad_u64_u32 v[8:9], s[10:11], s6, v8, 0
	v_add3_u32 v9, v9, v10, v11
	v_add_u32_e32 v10, 10, v40
	v_ashrrev_i32_e32 v11, 31, v10
	v_mul_lo_u32 v12, s6, v11
	v_mul_lo_u32 v13, s7, v10
	v_mad_u64_u32 v[10:11], s[10:11], s6, v10, 0
	v_add3_u32 v11, v11, v12, v13
	v_add_u32_e32 v12, 12, v40
	v_ashrrev_i32_e32 v13, 31, v12
	v_mul_lo_u32 v14, s6, v13
	v_mul_lo_u32 v15, s7, v12
	v_mad_u64_u32 v[12:13], s[10:11], s6, v12, 0
	v_add3_u32 v13, v13, v14, v15
	v_add_u32_e32 v14, 14, v40
	v_ashrrev_i32_e32 v15, 31, v14
	v_mul_lo_u32 v16, s6, v15
	v_mul_lo_u32 v17, s7, v14
	v_mad_u64_u32 v[14:15], s[10:11], s6, v14, 0
	v_lshl_add_u64 v[0:1], v[0:1], 2, v[24:25]
	v_lshl_add_u64 v[2:3], v[2:3], 2, v[24:25]
	v_lshl_add_u64 v[4:5], v[4:5], 2, v[24:25]
	v_lshl_add_u64 v[6:7], v[6:7], 2, v[24:25]
	v_lshl_add_u64 v[8:9], v[8:9], 2, v[24:25]
	v_add3_u32 v15, v15, v16, v17
	v_lshl_add_u64 v[10:11], v[10:11], 2, v[24:25]
	v_lshl_add_u64 v[12:13], v[12:13], 2, v[24:25]
	v_lshl_add_u64 v[14:15], v[14:15], 2, v[24:25]
	global_load_dword v0, v[0:1], off nt
	s_nop 0
	global_load_dword v1, v[2:3], off nt
	s_nop 0
	global_load_dword v2, v[4:5], off nt
	global_load_dword v3, v[6:7], off nt
	s_nop 0
	global_load_dword v4, v[8:9], off nt
	global_load_dword v5, v[10:11], off nt
	global_load_dword v6, v[12:13], off nt
	global_load_dword v7, v[14:15], off nt
	v_add_u32_e32 v8, 16, v40
	v_ashrrev_i32_e32 v9, 31, v8
	v_mul_lo_u32 v10, s6, v9
	v_mul_lo_u32 v11, s7, v8
	v_mad_u64_u32 v[8:9], s[10:11], s6, v8, 0
	v_add3_u32 v9, v9, v10, v11
	v_add_u32_e32 v10, 18, v40
	v_ashrrev_i32_e32 v11, 31, v10
	v_mul_lo_u32 v12, s6, v11
	v_mul_lo_u32 v13, s7, v10
	v_mad_u64_u32 v[10:11], s[10:11], s6, v10, 0
	v_add3_u32 v11, v11, v12, v13
	v_add_u32_e32 v12, 20, v40
	v_ashrrev_i32_e32 v13, 31, v12
	v_mul_lo_u32 v14, s6, v13
	v_mul_lo_u32 v15, s7, v12
	v_mad_u64_u32 v[12:13], s[10:11], s6, v12, 0
	v_add3_u32 v13, v13, v14, v15
	v_add_u32_e32 v14, 22, v40
	v_ashrrev_i32_e32 v15, 31, v14
	v_mul_lo_u32 v16, s6, v15
	v_mul_lo_u32 v17, s7, v14
	v_mad_u64_u32 v[14:15], s[10:11], s6, v14, 0
	v_add3_u32 v15, v15, v16, v17
	v_add_u32_e32 v16, 24, v40
	v_ashrrev_i32_e32 v17, 31, v16
	v_mul_lo_u32 v18, s6, v17
	v_mul_lo_u32 v19, s7, v16
	v_mad_u64_u32 v[16:17], s[10:11], s6, v16, 0
	v_add3_u32 v17, v17, v18, v19
	v_add_u32_e32 v18, 26, v40
	v_ashrrev_i32_e32 v19, 31, v18
	v_mul_lo_u32 v20, s6, v19
	v_mul_lo_u32 v21, s7, v18
	v_mad_u64_u32 v[18:19], s[10:11], s6, v18, 0
	v_add3_u32 v19, v19, v20, v21
	v_add_u32_e32 v20, 28, v40
	v_ashrrev_i32_e32 v21, 31, v20
	v_mul_lo_u32 v22, s6, v21
	v_mul_lo_u32 v23, s7, v20
	v_mad_u64_u32 v[20:21], s[10:11], s6, v20, 0
	v_add3_u32 v21, v21, v22, v23
	v_add_u32_e32 v22, 30, v40
	v_ashrrev_i32_e32 v23, 31, v22
	v_mul_lo_u32 v26, s6, v23
	v_mul_lo_u32 v27, s7, v22
	v_mad_u64_u32 v[22:23], s[10:11], s6, v22, 0
	v_add3_u32 v23, v23, v26, v27
	v_lshl_add_u64 v[8:9], v[8:9], 2, v[24:25]
	v_lshl_add_u64 v[10:11], v[10:11], 2, v[24:25]
	v_lshl_add_u64 v[12:13], v[12:13], 2, v[24:25]
	v_lshl_add_u64 v[14:15], v[14:15], 2, v[24:25]
	v_lshl_add_u64 v[16:17], v[16:17], 2, v[24:25]
	v_lshl_add_u64 v[18:19], v[18:19], 2, v[24:25]
	v_lshl_add_u64 v[20:21], v[20:21], 2, v[24:25]
	v_lshl_add_u64 v[22:23], v[22:23], 2, v[24:25]
	global_load_dword v8, v[8:9], off nt
	s_nop 0
	global_load_dword v9, v[10:11], off nt
	s_nop 0
	global_load_dword v10, v[12:13], off nt
	global_load_dword v11, v[14:15], off nt
	s_nop 0
	global_load_dword v12, v[16:17], off nt
	global_load_dword v13, v[18:19], off nt
	global_load_dword v14, v[20:21], off nt
	global_load_dword v15, v[22:23], off nt
	v_add_u32_e32 v16, 32, v40
	v_ashrrev_i32_e32 v17, 31, v16
	v_mul_lo_u32 v18, s6, v17
	v_mul_lo_u32 v19, s7, v16
	v_mad_u64_u32 v[16:17], s[10:11], s6, v16, 0
	v_add3_u32 v17, v17, v18, v19
	v_add_u32_e32 v18, 34, v40
	v_ashrrev_i32_e32 v19, 31, v18
	v_mul_lo_u32 v20, s6, v19
	v_mul_lo_u32 v21, s7, v18
	v_mad_u64_u32 v[18:19], s[10:11], s6, v18, 0
	v_add3_u32 v19, v19, v20, v21
	v_add_u32_e32 v20, 36, v40
	v_ashrrev_i32_e32 v21, 31, v20
	v_mul_lo_u32 v22, s6, v21
	v_mul_lo_u32 v23, s7, v20
	v_mad_u64_u32 v[20:21], s[10:11], s6, v20, 0
	v_add3_u32 v21, v21, v22, v23
	v_add_u32_e32 v22, 38, v40
	v_ashrrev_i32_e32 v23, 31, v22
	v_mul_lo_u32 v26, s6, v23
	v_mul_lo_u32 v27, s7, v22
	v_mad_u64_u32 v[22:23], s[10:11], s6, v22, 0
	v_add3_u32 v23, v23, v26, v27
	v_add_u32_e32 v26, 40, v40
	v_ashrrev_i32_e32 v27, 31, v26
	v_mul_lo_u32 v28, s6, v27
	v_mul_lo_u32 v29, s7, v26
; __device__ __forceinline__ void tr_load(const TrDesc& d, float (&v)[32], int lane) {
; #pragma unroll
;     for (int i = 0; i < 32; ++i) { const int kk = 2 * i + (lane >> 5); v[i] = d.W[(size_t)(d.k0 + kk) * d.ldw + d.n0 + (lane & 31)]; }
; }
; __global__ void __launch_bounds__(NTHREADS, 2) mega_fwd(Args a) {
;     ...
;         if (gw < NITEMS) {
;             TrDesc dc; P0_DESC(gw, dc); float vc[32]; tr_load(dc, vc, lane);
;             for (int it = gw; it < NITEMS; it += NGW) {
;                 TrDesc dn = dc; float vn[32];
	v_mad_u64_u32 v[26:27], s[10:11], s6, v26, 0
	v_add3_u32 v27, v27, v28, v29
	v_add_u32_e32 v28, 42, v40
	v_ashrrev_i32_e32 v29, 31, v28
	v_mul_lo_u32 v30, s6, v29
	v_mul_lo_u32 v31, s7, v28
	v_mad_u64_u32 v[28:29], s[10:11], s6, v28, 0
	v_add3_u32 v29, v29, v30, v31
	v_add_u32_e32 v30, 44, v40
	v_ashrrev_i32_e32 v31, 31, v30
	v_mul_lo_u32 v32, s6, v31
	v_mul_lo_u32 v33, s7, v30
	v_mad_u64_u32 v[30:31], s[10:11], s6, v30, 0
	v_add3_u32 v31, v31, v32, v33
	v_add_u32_e32 v32, 46, v40
	v_ashrrev_i32_e32 v33, 31, v32
	v_mul_lo_u32 v34, s6, v33
	v_mul_lo_u32 v35, s7, v32
	v_mad_u64_u32 v[32:33], s[10:11], s6, v32, 0
	v_add3_u32 v33, v33, v34, v35
	v_lshl_add_u64 v[16:17], v[16:17], 2, v[24:25]
	v_lshl_add_u64 v[18:19], v[18:19], 2, v[24:25]
	v_lshl_add_u64 v[20:21], v[20:21], 2, v[24:25]
	v_lshl_add_u64 v[22:23], v[22:23], 2, v[24:25]
	v_lshl_add_u64 v[26:27], v[26:27], 2, v[24:25]
	v_lshl_add_u64 v[28:29], v[28:29], 2, v[24:25]
	v_lshl_add_u64 v[30:31], v[30:31], 2, v[24:25]
	v_lshl_add_u64 v[32:33], v[32:33], 2, v[24:25]
	global_load_dword v16, v[16:17], off nt
	s_nop 0
	global_load_dword v17, v[18:19], off nt
	s_nop 0
	global_load_dword v18, v[20:21], off nt
	global_load_dword v19, v[22:23], off nt
	s_nop 0
	global_load_dword v20, v[26:27], off nt
	global_load_dword v21, v[28:29], off nt
	global_load_dword v22, v[30:31], off nt
	global_load_dword v23, v[32:33], off nt
	v_add_u32_e32 v26, 48, v40
	v_ashrrev_i32_e32 v27, 31, v26
	v_mul_lo_u32 v28, s6, v27
	v_mul_lo_u32 v29, s7, v26
	v_mad_u64_u32 v[26:27], s[10:11], s6, v26, 0
	v_add3_u32 v27, v27, v28, v29
	v_add_u32_e32 v28, 50, v40
	v_ashrrev_i32_e32 v29, 31, v28
	v_mul_lo_u32 v30, s6, v29
	v_mul_lo_u32 v31, s7, v28
	v_mad_u64_u32 v[28:29], s[10:11], s6, v28, 0
	v_add3_u32 v29, v29, v30, v31
	v_add_u32_e32 v30, 52, v40
	v_ashrrev_i32_e32 v31, 31, v30
	v_mul_lo_u32 v32, s6, v31
	v_mul_lo_u32 v33, s7, v30
	v_mad_u64_u32 v[30:31], s[10:11], s6, v30, 0
	v_add3_u32 v31, v31, v32, v33
	v_add_u32_e32 v32, 54, v40
	v_ashrrev_i32_e32 v33, 31, v32
	v_mul_lo_u32 v34, s6, v33
	v_mul_lo_u32 v35, s7, v32
	v_mad_u64_u32 v[32:33], s[10:11], s6, v32, 0
	v_add3_u32 v33, v33, v34, v35
	v_add_u32_e32 v34, 56, v40
	v_ashrrev_i32_e32 v35, 31, v34
	v_mul_lo_u32 v36, s6, v35
	v_mul_lo_u32 v37, s7, v34
	v_mad_u64_u32 v[34:35], s[10:11], s6, v34, 0
	v_add3_u32 v35, v35, v36, v37
	v_add_u32_e32 v36, 58, v40
	v_ashrrev_i32_e32 v37, 31, v36
	v_mul_lo_u32 v38, s6, v37
	v_mul_lo_u32 v39, s7, v36
	v_mad_u64_u32 v[36:37], s[10:11], s6, v36, 0
	v_add3_u32 v37, v37, v38, v39
	v_add_u32_e32 v38, 60, v40
	v_ashrrev_i32_e32 v39, 31, v38
	v_mul_lo_u32 v41, s6, v39
	v_mul_lo_u32 v42, s7, v38
	v_mad_u64_u32 v[38:39], s[10:11], s6, v38, 0
	v_add_u32_e32 v40, 62, v40
	v_add3_u32 v39, v39, v41, v42
	v_ashrrev_i32_e32 v41, 31, v40
	v_mul_lo_u32 v42, s6, v41
	v_mul_lo_u32 v43, s7, v40
	v_mad_u64_u32 v[40:41], s[6:7], s6, v40, 0
	v_lshl_add_u64 v[26:27], v[26:27], 2, v[24:25]
	v_lshl_add_u64 v[28:29], v[28:29], 2, v[24:25]
	v_lshl_add_u64 v[30:31], v[30:31], 2, v[24:25]
	v_add3_u32 v41, v41, v42, v43
	v_lshl_add_u64 v[32:33], v[32:33], 2, v[24:25]
	v_lshl_add_u64 v[34:35], v[34:35], 2, v[24:25]
	v_lshl_add_u64 v[36:37], v[36:37], 2, v[24:25]
	v_lshl_add_u64 v[38:39], v[38:39], 2, v[24:25]
	v_lshl_add_u64 v[40:41], v[40:41], 2, v[24:25]
	global_load_dword v24, v[26:27], off nt
	global_load_dword v25, v[28:29], off nt
	s_nop 0
	global_load_dword v26, v[30:31], off nt
	global_load_dword v27, v[32:33], off nt
	global_load_dword v28, v[34:35], off nt
	global_load_dword v29, v[36:37], off nt
	s_nop 0
	global_load_dword v30, v[38:39], off nt
	global_load_dword v31, v[40:41], off nt
	s_add_u32 s6, s28, 0x5600000
	s_addc_u32 s7, s29, 0
	v_writelane_b32 v249, s6, 26
	v_lshlrev_b32_e32 v32, 3, v197
	v_lshrrev_b32_e32 v69, 3, v196
	v_writelane_b32 v249, s7, 27
	s_add_u32 s6, s48, 0x2000
	s_addc_u32 s7, s49, 0
	v_writelane_b32 v249, s6, 28
	v_and_b32_e32 v32, 56, v32
	v_mul_u32_u24_e32 v35, 0x84, v32
	v_writelane_b32 v249, s7, 29
	s_add_u32 s6, s28, 0x5400000
	s_addc_u32 s7, s29, 0
	v_writelane_b32 v249, s6, 30
	v_lshlrev_b32_e32 v36, 2, v69
	v_add_u32_e32 v33, s5, v64
	v_writelane_b32 v249, s7, 31
	s_add_u32 s6, s78, 0x1000
	s_addc_u32 s7, s79, 0
	v_writelane_b32 v249, s6, 32
	v_add3_u32 v70, s5, v35, v36
	v_mul_u32_u24_e32 v34, 0x84, v68
	v_writelane_b32 v249, s7, 33
	s_add_u32 s6, s28, 0x5000000
	s_addc_u32 s7, s29, 0
	v_writelane_b32 v249, s6, 34
	v_add_u32_e32 v71, v33, v34
	v_lshlrev_b32_e32 v64, 1, v32
	v_writelane_b32 v249, s7, 35
	s_add_u32 s6, s28, 0x4e00000
	s_addc_u32 s7, s29, 0
	s_add_u32 s88, s28, 0x4d00000
	s_addc_u32 s89, s29, 0
	s_add_u32 s90, s80, 0x1000
	s_addc_u32 s91, s81, 0
	s_add_u32 s20, s28, 0x4a00000
	s_addc_u32 s21, s29, 0
	s_add_u32 s94, s80, 0x800
	s_addc_u32 s95, s81, 0
	s_add_u32 s65, s28, 0x800000
	v_writelane_b32 v249, s6, 36
	s_addc_u32 s66, s29, 0
	v_mov_b32_e32 v32, v65
	v_writelane_b32 v249, s7, 37
	s_add_u32 s6, s28, 0x3400000
	v_writelane_b32 v249, s6, 38
	s_addc_u32 s6, s29, 0
	s_add_i32 s5, s34, s33
	v_writelane_b32 v249, s6, 39
	s_lshl_b32 s6, s5, 1
	s_lshl_b32 s67, s5, 5
	s_lshl_b32 s12, s22, 8
	s_add_i32 s13, s6, 0x16500
	s_lshl_b32 s14, s22, 4
	s_lshl_b32 s15, s5, 2
	s_lshl_b32 s10, s22, 5
	s_lshl_b32 s11, s5, 6
	s_lshl_b32 s18, s22, 9
	v_mov_b32_e32 v33, v65
	v_mov_b32_e32 v34, v65
	v_mov_b32_e32 v35, v65
	v_mov_b32_e32 v36, v65
	v_mov_b32_e32 v37, v65
	v_mov_b32_e32 v38, v65
	v_mov_b32_e32 v39, v65
	v_mov_b32_e32 v40, v65
	v_mov_b32_e32 v41, v65
	v_mov_b32_e32 v42, v65
	v_mov_b32_e32 v43, v65
	v_mov_b32_e32 v44, v65
	v_mov_b32_e32 v45, v65
	v_mov_b32_e32 v46, v65
	v_mov_b32_e32 v47, v65
	v_mov_b32_e32 v48, v65
	v_mov_b32_e32 v49, v65
	v_mov_b32_e32 v50, v65
	v_mov_b32_e32 v51, v65
	v_mov_b32_e32 v52, v65
	v_mov_b32_e32 v53, v65
	v_mov_b32_e32 v54, v65
	v_mov_b32_e32 v55, v65
	v_mov_b32_e32 v56, v65
	v_mov_b32_e32 v57, v65
	v_mov_b32_e32 v58, v65
	v_mov_b32_e32 v59, v65
	v_mov_b32_e32 v60, v65
	v_mov_b32_e32 v61, v65
	v_mov_b32_e32 v62, v65
	v_mov_b32_e32 v63, v65
	v_lshlrev_b32_e32 v66, 2, v66
	s_mov_b32 s19, s34
	v_or_b32_e32 v72, 8, v69
	v_or_b32_e32 v73, 16, v69
	v_or_b32_e32 v74, 24, v69
	s_branch .LBB0_63

; __device__ __forceinline__ void tr_load(const TrDesc& d, float (&v)[32], int lane) {
; #pragma unroll
;     for (int i = 0; i < 32; ++i) { const int kk = 2 * i + (lane >> 5); v[i] = d.W[(size_t)(d.k0 + kk) * d.ldw + d.n0 + (lane & 31)]; }
; }
; __global__ void __launch_bounds__(NTHREADS, 2) mega_fwd(Args a) {
;     ...
;             for (int it = gw; it < NITEMS; it += NGW) {
;                 TrDesc dn = dc; float vn[32];
;                 const bool more = it + NGW < NITEMS;
;                 if (more) { P0_DESC(it + NGW, dn); tr_load(dn, vn, lane); }
.LBB0_103:
	s_ashr_i32 s55, s54, 31
	s_lshl_b64 s[54:55], s[54:55], 2
	v_add_u32_e32 v75, s16, v68
	s_add_u32 s54, s56, s54
	s_addc_u32 s55, s57, s55
	v_mov_b32_e32 v67, v65
	v_ashrrev_i32_e32 v32, 31, v75
	v_lshl_add_u64 v[56:57], s[54:55], 0, v[66:67]
	v_mul_lo_u32 v34, s52, v32
	v_mul_lo_u32 v35, s53, v75
	v_mad_u64_u32 v[32:33], s[54:55], s52, v75, 0
	v_add3_u32 v33, v33, v34, v35
	v_add_u32_e32 v34, 2, v75
	v_ashrrev_i32_e32 v35, 31, v34
	v_mul_lo_u32 v36, s52, v35
	v_mul_lo_u32 v37, s53, v34
	v_mad_u64_u32 v[34:35], s[54:55], s52, v34, 0
	v_add3_u32 v35, v35, v36, v37
	v_add_u32_e32 v36, 4, v75
	v_ashrrev_i32_e32 v37, 31, v36
	v_mul_lo_u32 v38, s52, v37
	v_mul_lo_u32 v39, s53, v36
	v_mad_u64_u32 v[36:37], s[54:55], s52, v36, 0
	v_add3_u32 v37, v37, v38, v39
	v_add_u32_e32 v38, 6, v75
	v_ashrrev_i32_e32 v39, 31, v38
	v_mul_lo_u32 v40, s52, v39
	v_mul_lo_u32 v41, s53, v38
	v_mad_u64_u32 v[38:39], s[54:55], s52, v38, 0
	v_add3_u32 v39, v39, v40, v41
	v_add_u32_e32 v40, 8, v75
	v_ashrrev_i32_e32 v41, 31, v40
	v_mul_lo_u32 v42, s52, v41
	v_mul_lo_u32 v43, s53, v40
	v_mad_u64_u32 v[40:41], s[54:55], s52, v40, 0
	v_add3_u32 v41, v41, v42, v43
	v_add_u32_e32 v42, 10, v75
	v_ashrrev_i32_e32 v43, 31, v42
	v_mul_lo_u32 v44, s52, v43
	v_mul_lo_u32 v45, s53, v42
	v_mad_u64_u32 v[42:43], s[54:55], s52, v42, 0
	v_add3_u32 v43, v43, v44, v45
	v_add_u32_e32 v44, 12, v75
	v_ashrrev_i32_e32 v45, 31, v44
	v_mul_lo_u32 v46, s52, v45
	v_mul_lo_u32 v47, s53, v44
	v_mad_u64_u32 v[44:45], s[54:55], s52, v44, 0
	v_add3_u32 v45, v45, v46, v47
	v_add_u32_e32 v46, 14, v75
	v_ashrrev_i32_e32 v47, 31, v46
	v_mul_lo_u32 v48, s52, v47
	v_mul_lo_u32 v49, s53, v46
	v_mad_u64_u32 v[46:47], s[54:55], s52, v46, 0
	v_lshl_add_u64 v[32:33], v[32:33], 2, v[56:57]
	v_lshl_add_u64 v[34:35], v[34:35], 2, v[56:57]
	v_lshl_add_u64 v[36:37], v[36:37], 2, v[56:57]
	v_lshl_add_u64 v[38:39], v[38:39], 2, v[56:57]
	v_lshl_add_u64 v[40:41], v[40:41], 2, v[56:57]
	v_add3_u32 v47, v47, v48, v49
	v_lshl_add_u64 v[42:43], v[42:43], 2, v[56:57]
	v_lshl_add_u64 v[44:45], v[44:45], 2, v[56:57]
	v_lshl_add_u64 v[46:47], v[46:47], 2, v[56:57]
	global_load_dword v32, v[32:33], off nt
	s_nop 0
	global_load_dword v33, v[34:35], off nt
	s_nop 0
	global_load_dword v34, v[36:37], off nt
	global_load_dword v35, v[38:39], off nt
	s_nop 0
	global_load_dword v36, v[40:41], off nt
	global_load_dword v37, v[42:43], off nt
	global_load_dword v38, v[44:45], off nt
	global_load_dword v39, v[46:47], off nt
	v_add_u32_e32 v40, 16, v75
	v_ashrrev_i32_e32 v41, 31, v40
	v_mul_lo_u32 v42, s52, v41
	v_mul_lo_u32 v43, s53, v40
	v_mad_u64_u32 v[40:41], s[54:55], s52, v40, 0
	v_add3_u32 v41, v41, v42, v43
	v_add_u32_e32 v42, 18, v75
	v_ashrrev_i32_e32 v43, 31, v42
	v_mul_lo_u32 v44, s52, v43
	v_mul_lo_u32 v45, s53, v42
	v_mad_u64_u32 v[42:43], s[54:55], s52, v42, 0
	v_add3_u32 v43, v43, v44, v45
	v_add_u32_e32 v44, 20, v75
	v_ashrrev_i32_e32 v45, 31, v44
	v_mul_lo_u32 v46, s52, v45
	v_mul_lo_u32 v47, s53, v44
	v_mad_u64_u32 v[44:45], s[54:55], s52, v44, 0
	v_add3_u32 v45, v45, v46, v47
	v_add_u32_e32 v46, 22, v75
	v_ashrrev_i32_e32 v47, 31, v46
	v_mul_lo_u32 v48, s52, v47
	v_mul_lo_u32 v49, s53, v46
	v_mad_u64_u32 v[46:47], s[54:55], s52, v46, 0
	v_add3_u32 v47, v47, v48, v49
	v_add_u32_e32 v48, 24, v75
	v_ashrrev_i32_e32 v49, 31, v48
	v_mul_lo_u32 v50, s52, v49
	v_mul_lo_u32 v51, s53, v48
	v_mad_u64_u32 v[48:49], s[54:55], s52, v48, 0
	v_add3_u32 v49, v49, v50, v51
	v_add_u32_e32 v50, 26, v75
	v_ashrrev_i32_e32 v51, 31, v50
	v_mul_lo_u32 v52, s52, v51
	v_mul_lo_u32 v53, s53, v50
	v_mad_u64_u32 v[50:51], s[54:55], s52, v50, 0
	v_add3_u32 v51, v51, v52, v53
	v_add_u32_e32 v52, 28, v75
	v_ashrrev_i32_e32 v53, 31, v52
	v_mul_lo_u32 v54, s52, v53
	v_mul_lo_u32 v55, s53, v52
	v_mad_u64_u32 v[52:53], s[54:55], s52, v52, 0
	v_add3_u32 v53, v53, v54, v55
	v_add_u32_e32 v54, 30, v75
	v_ashrrev_i32_e32 v55, 31, v54
	v_mul_lo_u32 v58, s52, v55
	v_mul_lo_u32 v59, s53, v54
	v_mad_u64_u32 v[54:55], s[54:55], s52, v54, 0
	v_lshl_add_u64 v[40:41], v[40:41], 2, v[56:57]
	v_lshl_add_u64 v[42:43], v[42:43], 2, v[56:57]
	v_lshl_add_u64 v[44:45], v[44:45], 2, v[56:57]
	v_lshl_add_u64 v[46:47], v[46:47], 2, v[56:57]
	v_lshl_add_u64 v[48:49], v[48:49], 2, v[56:57]
	v_add3_u32 v55, v55, v58, v59
	v_lshl_add_u64 v[50:51], v[50:51], 2, v[56:57]
	v_lshl_add_u64 v[52:53], v[52:53], 2, v[56:57]
	v_lshl_add_u64 v[54:55], v[54:55], 2, v[56:57]
	global_load_dword v40, v[40:41], off nt
	s_nop 0
	global_load_dword v41, v[42:43], off nt
	s_nop 0
	global_load_dword v42, v[44:45], off nt
	global_load_dword v43, v[46:47], off nt
	s_nop 0
	global_load_dword v44, v[48:49], off nt
	global_load_dword v45, v[50:51], off nt
; __device__ __forceinline__ void tr_load(const TrDesc& d, float (&v)[32], int lane) {
; #pragma unroll
;     for (int i = 0; i < 32; ++i) { const int kk = 2 * i + (lane >> 5); v[i] = d.W[(size_t)(d.k0 + kk) * d.ldw + d.n0 + (lane & 31)]; }
; }
	global_load_dword v46, v[52:53], off nt
	global_load_dword v47, v[54:55], off nt
	v_add_u32_e32 v48, 32, v75
	v_ashrrev_i32_e32 v49, 31, v48
	v_mul_lo_u32 v50, s52, v49
	v_mul_lo_u32 v51, s53, v48
	v_mad_u64_u32 v[48:49], s[54:55], s52, v48, 0
	v_add3_u32 v49, v49, v50, v51
	v_add_u32_e32 v50, 34, v75
	v_ashrrev_i32_e32 v51, 31, v50
	v_mul_lo_u32 v52, s52, v51
	v_mul_lo_u32 v53, s53, v50
	v_mad_u64_u32 v[50:51], s[54:55], s52, v50, 0
	v_add3_u32 v51, v51, v52, v53
	v_add_u32_e32 v52, 36, v75
	v_ashrrev_i32_e32 v53, 31, v52
	v_mul_lo_u32 v54, s52, v53
	v_mul_lo_u32 v55, s53, v52
	v_mad_u64_u32 v[52:53], s[54:55], s52, v52, 0
	v_add3_u32 v53, v53, v54, v55
	v_add_u32_e32 v54, 38, v75
	v_ashrrev_i32_e32 v55, 31, v54
	v_mul_lo_u32 v58, s52, v55
	v_mul_lo_u32 v59, s53, v54
	v_mad_u64_u32 v[54:55], s[54:55], s52, v54, 0
	v_add3_u32 v55, v55, v58, v59
	v_add_u32_e32 v58, 40, v75
	v_ashrrev_i32_e32 v59, 31, v58
	v_mul_lo_u32 v60, s52, v59
	v_mul_lo_u32 v61, s53, v58
	v_mad_u64_u32 v[58:59], s[54:55], s52, v58, 0
	v_add3_u32 v59, v59, v60, v61
	v_add_u32_e32 v60, 42, v75
	v_ashrrev_i32_e32 v61, 31, v60
	v_mul_lo_u32 v62, s52, v61
	v_mul_lo_u32 v63, s53, v60
	v_mad_u64_u32 v[60:61], s[54:55], s52, v60, 0
	v_add3_u32 v61, v61, v62, v63
	v_add_u32_e32 v62, 44, v75
	v_ashrrev_i32_e32 v63, 31, v62
	v_mul_lo_u32 v67, s52, v63
	v_mul_lo_u32 v76, s53, v62
	v_mad_u64_u32 v[62:63], s[54:55], s52, v62, 0
	v_add3_u32 v63, v63, v67, v76
	v_add_u32_e32 v67, 46, v75
	v_ashrrev_i32_e32 v76, 31, v67
	v_mul_lo_u32 v78, s52, v76
	v_mul_lo_u32 v79, s53, v67
	v_mad_u64_u32 v[76:77], s[54:55], s52, v67, 0
	v_lshl_add_u64 v[48:49], v[48:49], 2, v[56:57]
	v_lshl_add_u64 v[50:51], v[50:51], 2, v[56:57]
	v_lshl_add_u64 v[52:53], v[52:53], 2, v[56:57]
	v_lshl_add_u64 v[54:55], v[54:55], 2, v[56:57]
	v_lshl_add_u64 v[58:59], v[58:59], 2, v[56:57]
	v_add3_u32 v77, v77, v78, v79
	v_lshl_add_u64 v[60:61], v[60:61], 2, v[56:57]
	v_lshl_add_u64 v[62:63], v[62:63], 2, v[56:57]
	v_lshl_add_u64 v[76:77], v[76:77], 2, v[56:57]
	global_load_dword v48, v[48:49], off nt
	s_nop 0
	global_load_dword v49, v[50:51], off nt
	s_nop 0
	global_load_dword v50, v[52:53], off nt
	global_load_dword v51, v[54:55], off nt
	s_nop 0
	global_load_dword v52, v[58:59], off nt
	global_load_dword v53, v[60:61], off nt
	global_load_dword v54, v[62:63], off nt
	global_load_dword v55, v[76:77], off nt
	v_add_u32_e32 v58, 48, v75
	v_ashrrev_i32_e32 v59, 31, v58
	v_mul_lo_u32 v60, s52, v59
	v_mul_lo_u32 v61, s53, v58
	v_mad_u64_u32 v[58:59], s[54:55], s52, v58, 0
	v_add3_u32 v59, v59, v60, v61
	v_add_u32_e32 v60, 50, v75
	v_ashrrev_i32_e32 v61, 31, v60
	v_mul_lo_u32 v62, s52, v61
	v_mul_lo_u32 v63, s53, v60
	v_mad_u64_u32 v[60:61], s[54:55], s52, v60, 0
	v_add3_u32 v61, v61, v62, v63
	v_add_u32_e32 v62, 52, v75
	v_ashrrev_i32_e32 v63, 31, v62
	v_mul_lo_u32 v67, s52, v63
	v_mul_lo_u32 v76, s53, v62
	v_mad_u64_u32 v[62:63], s[54:55], s52, v62, 0
	v_add3_u32 v63, v63, v67, v76
	v_add_u32_e32 v67, 54, v75
	v_ashrrev_i32_e32 v76, 31, v67
	v_mul_lo_u32 v78, s52, v76
	v_mul_lo_u32 v79, s53, v67
	v_mad_u64_u32 v[76:77], s[54:55], s52, v67, 0
	v_add_u32_e32 v67, 56, v75
	v_add3_u32 v77, v77, v78, v79
	v_ashrrev_i32_e32 v78, 31, v67
	v_mul_lo_u32 v80, s52, v78
	v_mul_lo_u32 v81, s53, v67
	v_mad_u64_u32 v[78:79], s[54:55], s52, v67, 0
	v_add_u32_e32 v67, 58, v75
	v_add3_u32 v79, v79, v80, v81
	v_ashrrev_i32_e32 v80, 31, v67
	v_mul_lo_u32 v82, s52, v80
	v_mul_lo_u32 v83, s53, v67
	v_mad_u64_u32 v[80:81], s[54:55], s52, v67, 0
	v_add_u32_e32 v67, 60, v75
	v_add3_u32 v81, v81, v82, v83
	v_ashrrev_i32_e32 v82, 31, v67
	v_mul_lo_u32 v84, s52, v82
	v_mul_lo_u32 v85, s53, v67
	v_mad_u64_u32 v[82:83], s[54:55], s52, v67, 0
	v_add_u32_e32 v67, 62, v75
	v_ashrrev_i32_e32 v75, 31, v67
	v_add3_u32 v83, v83, v84, v85
	v_mul_lo_u32 v75, s52, v75
	v_mul_lo_u32 v86, s53, v67
	v_mad_u64_u32 v[84:85], s[52:53], s52, v67, 0
	v_lshl_add_u64 v[58:59], v[58:59], 2, v[56:57]
	v_lshl_add_u64 v[60:61], v[60:61], 2, v[56:57]
	v_lshl_add_u64 v[62:63], v[62:63], 2, v[56:57]
	v_add3_u32 v85, v85, v75, v86
	v_lshl_add_u64 v[76:77], v[76:77], 2, v[56:57]
	v_lshl_add_u64 v[78:79], v[78:79], 2, v[56:57]
	v_lshl_add_u64 v[80:81], v[80:81], 2, v[56:57]
	v_lshl_add_u64 v[82:83], v[82:83], 2, v[56:57]
	v_lshl_add_u64 v[84:85], v[84:85], 2, v[56:57]
	global_load_dword v56, v[58:59], off nt
	global_load_dword v57, v[60:61], off nt
	s_nop 0
	global_load_dword v58, v[62:63], off nt
	global_load_dword v59, v[76:77], off nt
	global_load_dword v60, v[78:79], off nt
	global_load_dword v61, v[80:81], off nt
	s_nop 0
	global_load_dword v62, v[82:83], off nt
	global_load_dword v63, v[84:85], off nt
